# stack: resident query fragments in sweeps + deferred queue-pop wait + 64-bit accumulator zeroing (on top of merged compaction atomic), later code offsets unchanged
# baseline (speedup 1.0000x reference)
;     ...
;         a0 = n0; a1 = n1;
;     }
.Lm6_nb15:
	s_mov_b64 exec, -1
	s_waitcnt vmcnt(0)
	v_mov_b64_e32 v[132:133], v[64:65]
	v_mov_b64_e32 v[134:135], v[66:67]
	v_mov_b64_e32 v[128:129], v[68:69]
	v_mov_b64_e32 v[130:131], v[70:71]
	s_cmp_lg_u32 s25, s1
	s_mov_b32 s18, s1
	s_cbranch_scc1 .Lm6_loop
	s_nop 0
	s_nop 0
	s_nop 0
	s_nop 0
	s_nop 0
	s_nop 0
